# v33: grid barrier: non-leader workgroups poll the cross-XCD release generation directly instead of waiting for their XCD leader to forward it (one poll hop less per barrier)
# speedup vs baseline: 1.0069x; 1.0069x over previous
.LBB0_393:
	s_or_b64 exec, exec, s[2:3]
	v_cvt_f32_u32_e32 v4, v2
	s_waitcnt vmcnt(0)
	v_readfirstlane_b32 s2, v3
	v_sub_u32_e32 v3, 0, v2
	v_rcp_iflag_f32_e32 v4, v4
	v_add_u32_e32 v5, s2, v1
	v_mul_f32_e32 v4, 0x4f7ffffe, v4
	v_cvt_u32_f32_e32 v4, v4
	v_mul_lo_u32 v1, v3, v4
	v_mul_hi_u32 v1, v4, v1
	v_add_u32_e32 v1, v4, v1
	v_mul_hi_u32 v1, v5, v1
	v_mul_lo_u32 v3, v1, v2
	v_sub_u32_e32 v3, v5, v3
	v_add_u32_e32 v4, 1, v1
	v_cmp_ge_u32_e32 vcc, v3, v2
	s_nop 1
	v_cndmask_b32_e32 v1, v1, v4, vcc
	v_sub_u32_e32 v4, v3, v2
	v_cndmask_b32_e32 v3, v3, v4, vcc
	v_add_u32_e32 v4, 1, v1
	v_cmp_ge_u32_e32 vcc, v3, v2
	v_add_u32_e32 v3, 1, v5
	s_nop 0
	v_cndmask_b32_e32 v1, v1, v4, vcc
	v_mul_lo_u32 v4, v2, v1
	v_add_u32_e32 v2, v4, v2
	v_cmp_ne_u32_e32 vcc, v3, v2
	s_and_saveexec_b64 s[2:3], vcc
	s_xor_b64 s[2:3], exec, s[2:3]
	s_cbranch_execz .LBB0_407
	v_readlane_b32 s6, v246, 45
	v_readlane_b32 s7, v246, 46
	s_waitcnt lgkmcnt(0)
	s_nop 3
	global_load_dword v0, v193, s[6:7] sc1
	s_waitcnt vmcnt(0)
	v_cmp_eq_u32_e32 vcc, v0, v1
	s_and_saveexec_b64 s[6:7], vcc
	s_cbranch_execz .LBB0_406
	s_mov_b32 s5, 1
	s_mov_b64 s[8:9], 0
	s_branch .LBB0_397

.LBB0_401:
	v_readlane_b32 s12, v246, 45
	v_readlane_b32 s13, v246, 46
	s_add_i32 s5, s5, 1
	s_mov_b64 s[14:15], -1
	s_nop 2
	global_load_dword v0, v193, s[12:13] sc1
	s_waitcnt vmcnt(0)
	v_cmp_ne_u32_e32 vcc, v0, v1
	s_orn2_b64 s[12:13], vcc, exec
	s_branch .LBB0_396
